# v25 + in-projection K-loop MFMAs ordered so consecutive MFMAs share neither the A nor the B fragment (bit-identical results)
# speedup vs baseline: 1.0017x; 1.0017x over previous
; #define PG8_STAGE(bufoff, gbase, voff) do { _Pragma("unroll") for (int _i = 0; _i < 2; ++_i) \
;         __builtin_amdgcn_global_load_lds((const unsigned*)((const char*)(gbase) + (voff)[_i]), (PG8_LAS unsigned*)(lds + (bufoff) + ldsw + _i * 8192), 16, 0, 0); } while (0)
; #define PG8_LDA(dst, b, h) do { _Pragma("unroll") for (int m = 0; m < 4; ++m) _Pragma("unroll") for (int k = 0; k < 2; ++k) dst[m][k] = *(const PG8_LAS bf16x8*)(lds + PG8_SA(b, h) + aoff + m * 2048 + k * 1024); } while (0)
; #define PG8_LDB(dst, b, h) do { _Pragma("unroll") for (int n = 0; n < 2; ++n) _Pragma("unroll") for (int k = 0; k < 2; ++k) dst[n][k] = *(const PG8_LAS bf16x8*)(lds + PG8_SB(b, h) + boff + n * 2048 + k * 1024); } while (0)
; #define PG8_MMA(ai, bj, At, Bt) do { __builtin_amdgcn_s_setprio(1); _Pragma("unroll") for (int m = 0; m < 4; ++m) _Pragma("unroll") for (int n = 0; n < 2; ++n) _Pragma("unroll") for (int k = 0; k < 2; ++k) \
;         acc[ai][bj][m][n] = __builtin_amdgcn_mfma_f32_16x16x32_bf16(Bt[n][k], At[m][k], acc[ai][bj][m][n], 0, 0, 0); __builtin_amdgcn_s_setprio(0); } while (0)
; #define PG8_WAIT_V(n) asm volatile("s_waitcnt vmcnt(" #n ")" ::: "memory")
; #define PG8_WAIT_L(n) asm volatile("s_waitcnt lgkmcnt(" #n ")" ::: "memory")
; template <class Epi, class Sched, bool ALIGN_EPI = false, bool SP2 = false>
; __device__ __forceinline__ void gemm_phase(PG8_LAS unsigned char* lds, const Gemm g, const Sched& S, const Epi& E, const int tid) {
;     ...
;             const bool last = (t == nt - 2);
;             const char* a1 = cA + (size_t)(t + 1) * kstep;
;             const char* a2 = last ? nA : cA + (size_t)(t + 2) * kstep; const char* b2 = last ? nB : cB + (size_t)(t + 2) * kstep;
;             const char* a3 = a2 + kstep; const char* b3 = b2 + kstep;
;             if (last && has_next) S.a_ready(nxt);
;             if constexpr (SP2) {
;             PG8_LDB(B0, 0, 0); PG8_LDB(B1, 0, 1); PG8_SCHED; PG8_LDA(At, 0, 0); PG8_STAGE(PG8_SA(1, 1), a1 + hstepA, voffA);
;             PG8_WAIT_V(8); PG8_WAIT_L(0); PG8_BAR; PG8_MMA(0, 0, At, B0); PG8_MMA(0, 1, At, B1); PG8_BAR; PG8_SCHED;
;             PG8_LDA(At, 0, 1); PG8_STAGE(PG8_SB(0, 0), b2, voffB); PG8_STAGE(PG8_SB(0, 1), b2 + hstepB, voffB); PG8_STAGE(PG8_SA(0, 0), a2, voffA);
;             PG8_WAIT_V(8); PG8_WAIT_L(0); PG8_BAR; PG8_MMA(1, 0, At, B0); PG8_MMA(1, 1, At, B1); PG8_BAR; PG8_SCHED;
.LBB0_175:
	s_add_u32 s22, s6, 0xfff80080
	s_addc_u32 s23, s7, -1
	s_add_i32 s60, 0, 0x10000
	s_cmp_eq_u32 s59, 28
	s_cselect_b32 s25, s17, s23
	s_cselect_b32 s24, s27, s22
	s_cselect_b32 s23, s15, s43
	s_cselect_b32 s22, s28, s29
	s_add_i32 s62, 0, 0x14000
	v_add_u32_e32 v140, s60, v225
	v_add_u32_e32 v156, s62, v225
	ds_read_b128 v[128:131], v140
	ds_read_b128 v[132:135], v140 offset:1024
	ds_read_b128 v[136:139], v140 offset:2048
	ds_read_b128 v[140:143], v140 offset:3072
	ds_read_b128 v[144:147], v156
	ds_read_b128 v[148:151], v156 offset:1024
	ds_read_b128 v[152:155], v156 offset:2048
	ds_read_b128 v[156:159], v156 offset:3072
	v_lshl_add_u64 v[202:203], s[6:7], 0, v[186:187]
	s_add_i32 m0, s46, 0xc000
	ds_read_b128 v[160:163], v226
	ds_read_b128 v[164:167], v226 offset:1024
	ds_read_b128 v[168:171], v226 offset:2048
	ds_read_b128 v[172:175], v226 offset:3072
	ds_read_b128 v[188:191], v226 offset:4096
	ds_read_b128 v[194:197], v226 offset:5120
	ds_read_b128 v[198:201], v226 offset:6144
	ds_read_b128 v[218:221], v226 offset:7168
	global_load_lds_dwordx4 v[202:203], off
	v_lshl_add_u64 v[202:203], s[6:7], 0, v[184:185]
	s_add_i32 m0, s46, 0xe000
	s_nop 0
	global_load_lds_dwordx4 v[202:203], off
	s_waitcnt vmcnt(8)
	s_waitcnt lgkmcnt(0)
	s_barrier
	s_setprio 1
	s_waitcnt lgkmcnt(0)
	v_mfma_f32_16x16x32_bf16 v[120:123], v[128:131], v[160:163], v[120:123]
	v_mfma_f32_16x16x32_bf16 v[60:63], v[136:139], v[168:171], v[60:63]
	v_mfma_f32_16x16x32_bf16 v[52:55], v[128:131], v[188:191], v[52:55]
	v_mfma_f32_16x16x32_bf16 v[24:27], v[136:139], v[198:201], v[24:27]
	v_mfma_f32_16x16x32_bf16 v[76:79], v[128:131], v[168:171], v[76:79]
	v_mfma_f32_16x16x32_bf16 v[112:115], v[136:139], v[160:163], v[112:115]
	v_mfma_f32_16x16x32_bf16 v[32:35], v[128:131], v[198:201], v[32:35]
	v_mfma_f32_16x16x32_bf16 v[36:39], v[136:139], v[188:191], v[36:39]
	v_mfma_f32_16x16x32_bf16 v[120:123], v[132:135], v[164:167], v[120:123]
	v_mfma_f32_16x16x32_bf16 v[60:63], v[140:143], v[172:175], v[60:63]
	v_mfma_f32_16x16x32_bf16 v[52:55], v[132:135], v[194:197], v[52:55]
	v_mfma_f32_16x16x32_bf16 v[24:27], v[140:143], v[218:221], v[24:27]
	v_mfma_f32_16x16x32_bf16 v[76:79], v[132:135], v[172:175], v[76:79]
	v_mfma_f32_16x16x32_bf16 v[112:115], v[140:143], v[164:167], v[112:115]
	v_mfma_f32_16x16x32_bf16 v[32:35], v[132:135], v[218:221], v[32:35]
	v_mfma_f32_16x16x32_bf16 v[36:39], v[140:143], v[194:197], v[36:39]
	s_setprio 0
	s_setprio 1
	v_mfma_f32_16x16x32_bf16 v[124:127], v[144:147], v[160:163], v[124:127]
	v_mfma_f32_16x16x32_bf16 v[68:71], v[152:155], v[168:171], v[68:71]
	v_mfma_f32_16x16x32_bf16 v[64:67], v[144:147], v[188:191], v[64:67]
	v_mfma_f32_16x16x32_bf16 v[28:31], v[152:155], v[198:201], v[28:31]
	v_mfma_f32_16x16x32_bf16 v[84:87], v[144:147], v[168:171], v[84:87]
	v_mfma_f32_16x16x32_bf16 v[116:119], v[152:155], v[160:163], v[116:119]
	v_mfma_f32_16x16x32_bf16 v[44:47], v[144:147], v[198:201], v[44:47]
	v_mfma_f32_16x16x32_bf16 v[48:51], v[152:155], v[188:191], v[48:51]
	v_mfma_f32_16x16x32_bf16 v[124:127], v[148:151], v[164:167], v[124:127]
	v_mfma_f32_16x16x32_bf16 v[68:71], v[156:159], v[172:175], v[68:71]
	v_mfma_f32_16x16x32_bf16 v[64:67], v[148:151], v[194:197], v[64:67]
	v_mfma_f32_16x16x32_bf16 v[28:31], v[156:159], v[218:221], v[28:31]
	v_mfma_f32_16x16x32_bf16 v[84:87], v[148:151], v[172:175], v[84:87]
	v_mfma_f32_16x16x32_bf16 v[116:119], v[156:159], v[164:167], v[116:119]
	v_mfma_f32_16x16x32_bf16 v[44:47], v[148:151], v[218:221], v[44:47]
	v_mfma_f32_16x16x32_bf16 v[48:51], v[156:159], v[194:197], v[48:51]
	s_setprio 0
	s_barrier
	s_add_i32 s60, s60, s37
	v_lshl_add_u64 v[202:203], s[22:23], 0, v[180:181]
	s_mov_b32 m0, s60
	ds_read_b128 v[160:163], v226 offset:16384
	ds_read_b128 v[164:167], v226 offset:17408
	ds_read_b128 v[168:171], v226 offset:18432
	ds_read_b128 v[172:175], v226 offset:19456
	ds_read_b128 v[188:191], v226 offset:20480
	ds_read_b128 v[194:197], v226 offset:21504
	ds_read_b128 v[198:201], v226 offset:22528
	ds_read_b128 v[218:221], v226 offset:23552
	global_load_lds_dwordx4 v[202:203], off
	s_add_i32 m0, s60, 0x2000
	s_add_u32 s60, s22, 0x80000
	v_lshl_add_u64 v[206:207], s[22:23], 0, v[176:177]
	s_addc_u32 s61, s23, 0
	s_add_i32 s62, s62, s37
	global_load_lds_dwordx4 v[206:207], off
	v_lshl_add_u64 v[208:209], s[60:61], 0, v[180:181]
	s_mov_b32 m0, s62
	v_lshl_add_u64 v[214:215], s[24:25], 0, v[178:179]
	global_load_lds_dwordx4 v[208:209], off
	v_lshl_add_u64 v[208:209], s[60:61], 0, v[176:177]
	s_add_i32 m0, s62, 0x2000
	s_nop 0
	global_load_lds_dwordx4 v[208:209], off
	v_lshl_add_u64 v[208:209], s[24:25], 0, v[182:183]
	s_mov_b32 m0, s46
	s_nop 0
	global_load_lds_dwordx4 v[208:209], off
	s_mov_b32 m0, s47
	s_nop 0
	global_load_lds_dwordx4 v[214:215], off
	s_waitcnt vmcnt(8)
	s_waitcnt lgkmcnt(0)
	s_barrier
; #define PG8_STAGE(bufoff, gbase, voff) do { _Pragma("unroll") for (int _i = 0; _i < 2; ++_i) \
;         __builtin_amdgcn_global_load_lds((const unsigned*)((const char*)(gbase) + (voff)[_i]), (PG8_LAS unsigned*)(lds + (bufoff) + ldsw + _i * 8192), 16, 0, 0); } while (0)
; #define PG8_LDA(dst, b, h) do { _Pragma("unroll") for (int m = 0; m < 4; ++m) _Pragma("unroll") for (int k = 0; k < 2; ++k) dst[m][k] = *(const PG8_LAS bf16x8*)(lds + PG8_SA(b, h) + aoff + m * 2048 + k * 1024); } while (0)
; #define PG8_LDB(dst, b, h) do { _Pragma("unroll") for (int n = 0; n < 2; ++n) _Pragma("unroll") for (int k = 0; k < 2; ++k) dst[n][k] = *(const PG8_LAS bf16x8*)(lds + PG8_SB(b, h) + boff + n * 2048 + k * 1024); } while (0)
; #define PG8_MMA(ai, bj, At, Bt) do { __builtin_amdgcn_s_setprio(1); _Pragma("unroll") for (int m = 0; m < 4; ++m) _Pragma("unroll") for (int n = 0; n < 2; ++n) _Pragma("unroll") for (int k = 0; k < 2; ++k) \
;         acc[ai][bj][m][n] = __builtin_amdgcn_mfma_f32_16x16x32_bf16(Bt[n][k], At[m][k], acc[ai][bj][m][n], 0, 0, 0); __builtin_amdgcn_s_setprio(0); } while (0)
; #define PG8_WAIT_V(n) asm volatile("s_waitcnt vmcnt(" #n ")" ::: "memory")
; #define PG8_WAIT_L(n) asm volatile("s_waitcnt lgkmcnt(" #n ")" ::: "memory")
; #define PG8_BAR __builtin_amdgcn_s_barrier()
; #define PG8_SCHED __builtin_amdgcn_sched_barrier(0)
; template <class Epi, class Sched, bool ALIGN_EPI = false, bool SP2 = false>
; __device__ __forceinline__ void gemm_phase(PG8_LAS unsigned char* lds, const Gemm g, const Sched& S, const Epi& E, const int tid) {
;     ...
;             PG8_WAIT_V(8); PG8_WAIT_L(0); PG8_BAR; PG8_MMA(1, 0, At, B0); PG8_MMA(1, 1, At, B1); PG8_BAR; PG8_SCHED;
;             PG8_LDB(B0, 1, 0); PG8_LDB(B1, 1, 1); PG8_SCHED; PG8_LDA(At, 1, 0); PG8_STAGE(PG8_SA(0, 1), a2 + hstepA, voffA);
;             PG8_WAIT_V(8); PG8_WAIT_L(0); PG8_BAR; PG8_MMA(0, 0, At, B0); PG8_MMA(0, 1, At, B1); PG8_BAR; PG8_SCHED;
	s_setprio 1
	s_waitcnt lgkmcnt(0)
	v_mfma_f32_16x16x32_bf16 v[96:99], v[128:131], v[160:163], v[96:99]
	v_mfma_f32_16x16x32_bf16 v[80:83], v[136:139], v[168:171], v[80:83]
	v_mfma_f32_16x16x32_bf16 v[16:19], v[128:131], v[188:191], v[16:19]
	v_mfma_f32_16x16x32_bf16 v[4:7], v[136:139], v[198:201], v[4:7]
	v_mfma_f32_16x16x32_bf16 v[72:75], v[128:131], v[168:171], v[72:75]
	v_mfma_f32_16x16x32_bf16 v[100:103], v[136:139], v[160:163], v[100:103]
	v_mfma_f32_16x16x32_bf16 v[0:3], v[128:131], v[198:201], v[0:3]
	v_mfma_f32_16x16x32_bf16 v[20:23], v[136:139], v[188:191], v[20:23]
	v_mfma_f32_16x16x32_bf16 v[96:99], v[132:135], v[164:167], v[96:99]
	v_mfma_f32_16x16x32_bf16 v[80:83], v[140:143], v[172:175], v[80:83]
	v_mfma_f32_16x16x32_bf16 v[16:19], v[132:135], v[194:197], v[16:19]
	v_mfma_f32_16x16x32_bf16 v[4:7], v[140:143], v[218:221], v[4:7]
	v_mfma_f32_16x16x32_bf16 v[72:75], v[132:135], v[172:175], v[72:75]
	v_mfma_f32_16x16x32_bf16 v[100:103], v[140:143], v[164:167], v[100:103]
	v_mfma_f32_16x16x32_bf16 v[0:3], v[132:135], v[218:221], v[0:3]
	v_mfma_f32_16x16x32_bf16 v[20:23], v[140:143], v[194:197], v[20:23]
	s_setprio 0
	s_setprio 1
	v_mfma_f32_16x16x32_bf16 v[108:111], v[144:147], v[160:163], v[108:111]
	v_mfma_f32_16x16x32_bf16 v[88:91], v[152:155], v[168:171], v[88:91]
	v_mfma_f32_16x16x32_bf16 v[56:59], v[144:147], v[188:191], v[56:59]
	v_mfma_f32_16x16x32_bf16 v[12:15], v[152:155], v[198:201], v[12:15]
	v_mfma_f32_16x16x32_bf16 v[92:95], v[144:147], v[168:171], v[92:95]
	v_mfma_f32_16x16x32_bf16 v[104:107], v[152:155], v[160:163], v[104:107]
	v_mfma_f32_16x16x32_bf16 v[8:11], v[144:147], v[198:201], v[8:11]
	v_mfma_f32_16x16x32_bf16 v[40:43], v[152:155], v[188:191], v[40:43]
	v_mfma_f32_16x16x32_bf16 v[108:111], v[148:151], v[164:167], v[108:111]
	v_mfma_f32_16x16x32_bf16 v[88:91], v[156:159], v[172:175], v[88:91]
	v_mfma_f32_16x16x32_bf16 v[56:59], v[148:151], v[194:197], v[56:59]
	v_mfma_f32_16x16x32_bf16 v[12:15], v[156:159], v[218:221], v[12:15]
	v_mfma_f32_16x16x32_bf16 v[92:95], v[148:151], v[172:175], v[92:95]
	v_mfma_f32_16x16x32_bf16 v[104:107], v[156:159], v[164:167], v[104:107]
	v_mfma_f32_16x16x32_bf16 v[8:11], v[148:151], v[218:221], v[8:11]
	v_mfma_f32_16x16x32_bf16 v[40:43], v[156:159], v[194:197], v[40:43]
	s_setprio 0
	s_barrier
	s_add_i32 s60, 0, 0x18000
	s_add_i32 s61, 0, 0x1c000
	v_add_u32_e32 v140, s60, v225
	v_add_u32_e32 v156, s61, v225
	ds_read_b128 v[128:131], v140
	ds_read_b128 v[132:135], v140 offset:1024
	ds_read_b128 v[136:139], v140 offset:2048
	ds_read_b128 v[140:143], v140 offset:3072
	ds_read_b128 v[144:147], v156
	ds_read_b128 v[148:151], v156 offset:1024
	ds_read_b128 v[152:155], v156 offset:2048
	ds_read_b128 v[156:159], v156 offset:3072
	s_add_u32 s24, s24, 0x80000
	s_addc_u32 s25, s25, 0
	s_mov_b32 m0, s48
	v_lshl_add_u64 v[216:217], s[24:25], 0, v[182:183]
	ds_read_b128 v[160:163], v226 offset:32768
	ds_read_b128 v[164:167], v226 offset:33792
	ds_read_b128 v[168:171], v226 offset:34816
	ds_read_b128 v[172:175], v226 offset:35840
	ds_read_b128 v[188:191], v226 offset:36864
	ds_read_b128 v[194:197], v226 offset:37888
	ds_read_b128 v[198:201], v226 offset:38912
	ds_read_b128 v[218:221], v226 offset:39936
	global_load_lds_dwordx4 v[216:217], off
	v_lshl_add_u64 v[216:217], s[24:25], 0, v[178:179]
	s_mov_b32 m0, s49
	s_nop 0
	global_load_lds_dwordx4 v[216:217], off
	s_waitcnt vmcnt(8)
	s_waitcnt lgkmcnt(0)
	s_barrier
	s_setprio 1
	s_waitcnt lgkmcnt(0)
	v_mfma_f32_16x16x32_bf16 v[120:123], v[128:131], v[160:163], v[120:123]
	v_mfma_f32_16x16x32_bf16 v[60:63], v[136:139], v[168:171], v[60:63]
	v_mfma_f32_16x16x32_bf16 v[52:55], v[128:131], v[188:191], v[52:55]
	v_mfma_f32_16x16x32_bf16 v[24:27], v[136:139], v[198:201], v[24:27]
	v_mfma_f32_16x16x32_bf16 v[76:79], v[128:131], v[168:171], v[76:79]
	v_mfma_f32_16x16x32_bf16 v[112:115], v[136:139], v[160:163], v[112:115]
	v_mfma_f32_16x16x32_bf16 v[32:35], v[128:131], v[198:201], v[32:35]
	v_mfma_f32_16x16x32_bf16 v[36:39], v[136:139], v[188:191], v[36:39]
	v_mfma_f32_16x16x32_bf16 v[120:123], v[132:135], v[164:167], v[120:123]
	v_mfma_f32_16x16x32_bf16 v[60:63], v[140:143], v[172:175], v[60:63]
	v_mfma_f32_16x16x32_bf16 v[52:55], v[132:135], v[194:197], v[52:55]
	v_mfma_f32_16x16x32_bf16 v[24:27], v[140:143], v[218:221], v[24:27]
	v_mfma_f32_16x16x32_bf16 v[76:79], v[132:135], v[172:175], v[76:79]
	v_mfma_f32_16x16x32_bf16 v[112:115], v[140:143], v[164:167], v[112:115]
	v_mfma_f32_16x16x32_bf16 v[32:35], v[132:135], v[218:221], v[32:35]
	v_mfma_f32_16x16x32_bf16 v[36:39], v[140:143], v[194:197], v[36:39]
	s_setprio 0
	s_setprio 1
	v_mfma_f32_16x16x32_bf16 v[124:127], v[144:147], v[160:163], v[124:127]
	v_mfma_f32_16x16x32_bf16 v[68:71], v[152:155], v[168:171], v[68:71]
	v_mfma_f32_16x16x32_bf16 v[64:67], v[144:147], v[188:191], v[64:67]
	v_mfma_f32_16x16x32_bf16 v[28:31], v[152:155], v[198:201], v[28:31]
	v_mfma_f32_16x16x32_bf16 v[84:87], v[144:147], v[168:171], v[84:87]
	v_mfma_f32_16x16x32_bf16 v[116:119], v[152:155], v[160:163], v[116:119]
	v_mfma_f32_16x16x32_bf16 v[44:47], v[144:147], v[198:201], v[44:47]
	v_mfma_f32_16x16x32_bf16 v[48:51], v[152:155], v[188:191], v[48:51]
	v_mfma_f32_16x16x32_bf16 v[124:127], v[148:151], v[164:167], v[124:127]
	v_mfma_f32_16x16x32_bf16 v[68:71], v[156:159], v[172:175], v[68:71]
	v_mfma_f32_16x16x32_bf16 v[64:67], v[148:151], v[194:197], v[64:67]
	v_mfma_f32_16x16x32_bf16 v[28:31], v[156:159], v[218:221], v[28:31]
	v_mfma_f32_16x16x32_bf16 v[84:87], v[148:151], v[172:175], v[84:87]
	v_mfma_f32_16x16x32_bf16 v[116:119], v[156:159], v[164:167], v[116:119]
	v_mfma_f32_16x16x32_bf16 v[44:47], v[148:151], v[218:221], v[44:47]
	v_mfma_f32_16x16x32_bf16 v[48:51], v[156:159], v[194:197], v[48:51]
	s_setprio 0
	s_barrier
; #define PG8_STAGE(bufoff, gbase, voff) do { _Pragma("unroll") for (int _i = 0; _i < 2; ++_i) \
;         __builtin_amdgcn_global_load_lds((const unsigned*)((const char*)(gbase) + (voff)[_i]), (PG8_LAS unsigned*)(lds + (bufoff) + ldsw + _i * 8192), 16, 0, 0); } while (0)
; #define PG8_LDA(dst, b, h) do { _Pragma("unroll") for (int m = 0; m < 4; ++m) _Pragma("unroll") for (int k = 0; k < 2; ++k) dst[m][k] = *(const PG8_LAS bf16x8*)(lds + PG8_SA(b, h) + aoff + m * 2048 + k * 1024); } while (0)
; #define PG8_MMA(ai, bj, At, Bt) do { __builtin_amdgcn_s_setprio(1); _Pragma("unroll") for (int m = 0; m < 4; ++m) _Pragma("unroll") for (int n = 0; n < 2; ++n) _Pragma("unroll") for (int k = 0; k < 2; ++k) \
;         acc[ai][bj][m][n] = __builtin_amdgcn_mfma_f32_16x16x32_bf16(Bt[n][k], At[m][k], acc[ai][bj][m][n], 0, 0, 0); __builtin_amdgcn_s_setprio(0); } while (0)
; #define PG8_WAIT_V(n) asm volatile("s_waitcnt vmcnt(" #n ")" ::: "memory")
; #define PG8_WAIT_L(n) asm volatile("s_waitcnt lgkmcnt(" #n ")" ::: "memory")
; #define PG8_BAR __builtin_amdgcn_s_barrier()
; #define PG8_SCHED __builtin_amdgcn_sched_barrier(0)
; template <class Epi, class Sched, bool ALIGN_EPI = false, bool SP2 = false>
; __device__ __forceinline__ void gemm_phase(PG8_LAS unsigned char* lds, const Gemm g, const Sched& S, const Epi& E, const int tid) {
;     ...
;             PG8_LDA(At, 1, 1); PG8_STAGE(PG8_SB(1, 0), b3, voffB); PG8_STAGE(PG8_SB(1, 1), b3 + hstepB, voffB); PG8_STAGE(PG8_SA(1, 0), a3, voffA);
;             PG8_WAIT_V(8); PG8_WAIT_L(0); PG8_BAR; PG8_MMA(1, 0, At, B0); PG8_MMA(1, 1, At, B1); PG8_BAR; PG8_SCHED;
	s_add_i32 s24, s60, s37
	v_lshl_add_u64 v[202:203], v[202:203], 0, s[82:83]
	s_mov_b32 m0, s24
	ds_read_b128 v[160:163], v226 offset:49152
	ds_read_b128 v[164:167], v226 offset:50176
	ds_read_b128 v[168:171], v226 offset:51200
	ds_read_b128 v[172:175], v226 offset:52224
	ds_read_b128 v[188:191], v226 offset:53248
	ds_read_b128 v[194:197], v226 offset:54272
	ds_read_b128 v[198:201], v226 offset:55296
	ds_read_b128 v[218:221], v226 offset:56320
	global_load_lds_dwordx4 v[202:203], off
	s_add_i32 m0, s24, 0x2000
	s_add_u32 s22, s22, 0x80080
	v_lshl_add_u64 v[202:203], v[206:207], 0, s[82:83]
	s_addc_u32 s23, s23, 0
	s_add_i32 s24, s61, s37
	global_load_lds_dwordx4 v[202:203], off
	v_lshl_add_u64 v[202:203], s[22:23], 0, v[180:181]
	s_mov_b32 m0, s24
	s_nop 0
	global_load_lds_dwordx4 v[202:203], off
	v_lshl_add_u64 v[202:203], s[22:23], 0, v[176:177]
	s_add_i32 m0, s24, 0x2000
	s_nop 0
	global_load_lds_dwordx4 v[202:203], off
	v_lshl_add_u64 v[202:203], v[208:209], 0, s[82:83]
	s_mov_b32 m0, s54
	s_nop 0
	global_load_lds_dwordx4 v[202:203], off
	v_lshl_add_u64 v[202:203], v[214:215], 0, s[82:83]
	s_mov_b32 m0, s55
	s_nop 0
	global_load_lds_dwordx4 v[202:203], off
	s_waitcnt vmcnt(8)
	s_waitcnt lgkmcnt(0)
	s_barrier
	s_setprio 1
	s_waitcnt lgkmcnt(0)
	v_mfma_f32_16x16x32_bf16 v[96:99], v[128:131], v[160:163], v[96:99]
	v_mfma_f32_16x16x32_bf16 v[80:83], v[136:139], v[168:171], v[80:83]
	v_mfma_f32_16x16x32_bf16 v[16:19], v[128:131], v[188:191], v[16:19]
	v_mfma_f32_16x16x32_bf16 v[4:7], v[136:139], v[198:201], v[4:7]
	v_mfma_f32_16x16x32_bf16 v[72:75], v[128:131], v[168:171], v[72:75]
	v_mfma_f32_16x16x32_bf16 v[100:103], v[136:139], v[160:163], v[100:103]
	v_mfma_f32_16x16x32_bf16 v[0:3], v[128:131], v[198:201], v[0:3]
	v_mfma_f32_16x16x32_bf16 v[20:23], v[136:139], v[188:191], v[20:23]
	v_mfma_f32_16x16x32_bf16 v[96:99], v[132:135], v[164:167], v[96:99]
	v_mfma_f32_16x16x32_bf16 v[80:83], v[140:143], v[172:175], v[80:83]
	v_mfma_f32_16x16x32_bf16 v[16:19], v[132:135], v[194:197], v[16:19]
	v_mfma_f32_16x16x32_bf16 v[4:7], v[140:143], v[218:221], v[4:7]
	v_mfma_f32_16x16x32_bf16 v[72:75], v[132:135], v[172:175], v[72:75]
	v_mfma_f32_16x16x32_bf16 v[100:103], v[140:143], v[164:167], v[100:103]
	v_mfma_f32_16x16x32_bf16 v[0:3], v[132:135], v[218:221], v[0:3]
	v_mfma_f32_16x16x32_bf16 v[20:23], v[140:143], v[194:197], v[20:23]
	s_setprio 0
	s_setprio 1
	v_mfma_f32_16x16x32_bf16 v[108:111], v[144:147], v[160:163], v[108:111]
	v_mfma_f32_16x16x32_bf16 v[88:91], v[152:155], v[168:171], v[88:91]
	v_mfma_f32_16x16x32_bf16 v[56:59], v[144:147], v[188:191], v[56:59]
	v_mfma_f32_16x16x32_bf16 v[12:15], v[152:155], v[198:201], v[12:15]
	v_mfma_f32_16x16x32_bf16 v[92:95], v[144:147], v[168:171], v[92:95]
	v_mfma_f32_16x16x32_bf16 v[104:107], v[152:155], v[160:163], v[104:107]
	v_mfma_f32_16x16x32_bf16 v[8:11], v[144:147], v[198:201], v[8:11]
	v_mfma_f32_16x16x32_bf16 v[40:43], v[152:155], v[188:191], v[40:43]
	v_mfma_f32_16x16x32_bf16 v[108:111], v[148:151], v[164:167], v[108:111]
	v_mfma_f32_16x16x32_bf16 v[88:91], v[156:159], v[172:175], v[88:91]
	v_mfma_f32_16x16x32_bf16 v[56:59], v[148:151], v[194:197], v[56:59]
	v_mfma_f32_16x16x32_bf16 v[12:15], v[156:159], v[218:221], v[12:15]
	v_mfma_f32_16x16x32_bf16 v[92:95], v[148:151], v[172:175], v[92:95]
	v_mfma_f32_16x16x32_bf16 v[104:107], v[156:159], v[164:167], v[104:107]
	v_mfma_f32_16x16x32_bf16 v[8:11], v[148:151], v[218:221], v[8:11]
	v_mfma_f32_16x16x32_bf16 v[40:43], v[156:159], v[194:197], v[40:43]
	s_setprio 0
	s_barrier
	s_add_i32 s59, s59, 2
	s_add_u32 s29, s29, 0x100
	s_addc_u32 s43, s43, 0
	s_add_u32 s6, s6, 0x100
	s_addc_u32 s7, s7, 0
	s_cmp_gt_u32 s59, 29
	s_cbranch_scc0 .LBB0_175
	s_and_b64 vcc, exec, s[12:13]
	s_cbranch_vccz .LBB0_178
	s_barrier
